# MLA / diff K,V staging loads through scalar bases + 32-bit lane offsets (no per-lane 64-bit VALU pointer arithmetic in the tile loops)
# speedup vs baseline: 1.0083x; 1.0083x over previous
; template <int DQK, int DV, int FLAGS, int qp, int kp, int vts, int op> ...
;     ...
;     u32x4 kreg[KPT], vreg[VPT];
;     unsigned kgo[KPT], vgo[VPT], klo[KPT], vlo[VPT];
; #pragma unroll
;     for (int i = 0; i < KPT; ++i) { const int c = tid + i * NTHREADS; const int row = c / KC, cc = c % KC; kgo[i] = (unsigned)(row * kp + cc * 8) * 2u; klo[i] = (unsigned)(row * KROW + cc * 16); }
; #pragma unroll
;     for (int i = 0; i < VPT; ++i) { const int c = tid + i * NTHREADS; const int d = c >> 3, cc = c & 7; vgo[i] = (unsigned)(d * vts + cc * 8) * 2u; vlo[i] = (unsigned)(KT_BYTES + d * VROW + cc * 16); }
;     ...
;     ATT_GLOAD((FLAGS & AF_REV) ? kt_hi - 1 : kt_lo); ATT_LSTORE(0);
;     __syncthreads();
;     bool started = false;
;     const int prow = (r32 & ~12) | ((r32 & 4) << 1) | ((r32 & 8) >> 1);
;     const int ntile = kt_hi - kt_lo;
;     for (int it = 0; it < ntile; ++it) {
;         const int t = (FLAGS & AF_REV) ? kt_hi - 1 - it : kt_lo + it;
;         const int cur = it & 1;
;         const bool more = (it + 1 < ntile);
;         const int kv0 = t * 64;
;         bool skip = false;
;         if (FLAGS & AF_CAUSAL) skip = skip || (kv0 > qmax_w);
;         if (FLAGS & AF_WINDOW) skip = skip || (kv0 + 63 < qmin_w - (SWA_W - 1));
;         if (!skip) {
;             const LAS unsigned char* kb = lds + cur * BUF + prow * KROW + 16 * hi;
;             const LAS unsigned char* vb = lds + cur * BUF + KT_BYTES + r32 * VROW + 16 * hi;
;             f32x16 p0, p1;
;             bf16x8 kf[2][4];
; #pragma unroll
;             for (int i = 0; i < 2; ++i) { kf[0][2 * i] = *(const LAS bf16x8*)(kb + i * 32); kf[0][2 * i + 1] = *(const LAS bf16x8*)(kb + 32 * KROW + i * 32); }
;             const int nrel = qpos - kv0 - 8 * hi;
;             if (FLAGS & AF_ALIBI) { const float ab = -slope2 * (float)nrel - ((FLAGS & AF_ROBUST) ? 0.f : m);
; #pragma unroll
;                 for (int r = 0; r < 16; ++r) { const float c = (float)(16 * (r >> 3) + (r & 7)); p0[r] = __builtin_fmaf(slope2, c, ab); p1[r] = __builtin_fmaf(slope2, c + 32.f, ab); }
;             } else if (FLAGS & AF_ROBUST) {
; #pragma unroll
;                 for (int r = 0; r < 16; ++r) { p0[r] = 0.f; p1[r] = 0.f; }
;             } else { p0 = negm; p1 = negm; }
;             __builtin_amdgcn_sched_barrier(0);
; #pragma unroll
;             for (int c = 0; c < ND0 / 2; ++c) {
;                 if (c + 1 < ND0 / 2) {
.LBB0_536:
	s_andn2_b64 vcc, exec, s[12:13]
	v_lshlrev_b32_e32 v170, 3, v19
	s_cbranch_vccnz .LBB0_524
	s_and_b32 s87, s19, 0xffffffe0
	s_add_i32 s16, s16, s17
	s_add_i32 s87, s87, s3
	s_lshl_b32 s15, s2, 2
	s_lshl_b32 s12, s16, 17
	s_or_b32 s88, s87, 31
	s_add_i32 s2, s15, 4
	s_bfe_u32 s17, s16, 0x30004
	s_and_b32 s12, s12, 0xe00000
	s_add_u32 s12, s14, s12
	s_addc_u32 s13, 0, 0
	s_add_u32 s12, s93, s12
	v_readlane_b32 s14, v252, 61
	v_mov_b32_e32 v21, v1
	s_addc_u32 s13, s14, s13
	s_mulk_i32 s17, 0xc0
	v_and_b32_e32 v22, 31, v17
	v_and_b32_e32 v19, 19, v17
	v_lshlrev_b32_e32 v23, 1, v17
	v_lshrrev_b32_e32 v17, 1, v17
	v_lshl_add_u64 v[176:177], s[12:13], 0, v[20:21]
	s_add_u32 s12, s18, s17
	v_and_b32_e32 v23, 8, v23
	v_and_b32_e32 v17, 4, v17
	s_addc_u32 s13, 0, 0
	v_readlane_b32 s14, v252, 63
	v_or3_b32 v17, v19, v23, v17
	s_add_u32 s12, s14, s12
	v_readlane_b32 s14, v253, 1
	v_mul_u32_u24_e32 v169, 0xd0, v17
	v_mul_u32_u24_e32 v171, 0x90, v22
	v_mov_b32_e32 v17, v1
	v_mov_b32_e32 v19, v1
	v_add_u32_e32 v22, s87, v22
	s_addc_u32 s13, s14, s13
	v_mov_b32_e32 v32, v1
	v_mov_b32_e32 v33, v1
	v_sub_u32_e32 v173, v22, v170
	v_lshl_add_u64 v[178:179], s[12:13], 0, v[16:17]
	v_lshl_add_u64 v[180:181], s[12:13], 0, v[18:19]
	v_mov_b32_e32 v34, v1
	v_mov_b32_e32 v35, v1
	v_mov_b32_e32 v36, v1
	v_mov_b32_e32 v37, v1
	v_mov_b32_e32 v38, v1
	v_mov_b32_e32 v39, v1
	v_mov_b32_e32 v40, v1
	v_mov_b32_e32 v41, v1
	v_mov_b32_e32 v42, v1
	v_mov_b32_e32 v43, v1
	v_mov_b32_e32 v44, v1
	v_mov_b32_e32 v45, v1
	v_mov_b32_e32 v46, v1
	v_mov_b32_e32 v47, v1
	v_mov_b32_e32 v183, 0
	v_mov_b64_e32 v[16:17], v[32:33]
	s_mov_b64 s[0:1], s[90:91]
	s_mov_b32 s3, 1
	s_xor_b32 s90, s15, -4
	s_mov_b64 s[82:83], 0
	s_mov_b32 s91, 63
	v_mov_b64_e32 v[18:19], v[34:35]
	v_mov_b64_e32 v[20:21], v[36:37]
	v_mov_b64_e32 v[22:23], v[38:39]
	v_mov_b64_e32 v[24:25], v[40:41]
	v_mov_b64_e32 v[26:27], v[42:43]
	v_mov_b64_e32 v[28:29], v[44:45]
	v_mov_b64_e32 v[30:31], v[46:47]
	v_mov_b32_e32 v175, 0
	v_mov_b32_e32 v48, 0
	v_mov_b32_e32 v49, v183
	v_mov_b32_e32 v50, v183
	v_mov_b32_e32 v51, v183
	v_mov_b32_e32 v52, v183
	v_mov_b32_e32 v53, v183
	v_mov_b32_e32 v54, v183
	v_mov_b32_e32 v55, v183
	v_mov_b32_e32 v56, v183
	v_mov_b32_e32 v57, v183
	v_mov_b32_e32 v58, v183
	v_mov_b32_e32 v59, v183
	v_mov_b32_e32 v60, v183
	v_mov_b32_e32 v61, v183
	v_mov_b32_e32 v62, v183
	v_mov_b32_e32 v63, v183
	s_andn2_b64 vcc, exec, s[4:5]
	s_cbranch_vccnz .Lq_fallback
	v_readfirstlane_b32 s98, v178
	v_readfirstlane_b32 s99, v179
	v_readfirstlane_b32 s100, v176
	v_readfirstlane_b32 s101, v177
	s_nop 1
	v_subrev_u32_e32 v178, s98, v178
	v_subrev_u32_e32 v180, s98, v180
	v_subrev_u32_e32 v176, s100, v176
	s_movk_i32 s16, 0x5800
	s_waitcnt vmcnt(0)
	v_add_u32_e32 v209, s16, v14
	v_add_u32_e32 v210, s16, v174
	v_add_u32_e32 v211, s16, v172
	ds_write_b128 v209, v[214:217]
	ds_write_b128 v210, v[222:225] offset:13312
	s_and_saveexec_b64 s[14:15], s[10:11]
	ds_write_b128 v211, v[218:221]
	s_or_b64 exec, exec, s[14:15]
	s_add_u32 s98, s98, s96
	s_addc_u32 s99, s99, s97
	s_add_u32 s100, s100, 0x80
	s_addc_u32 s101, s101, 0
	s_and_saveexec_b64 s[14:15], s[10:11]
	global_load_dwordx4 v[144:147], v180, s[98:99]
	s_or_b64 exec, exec, s[14:15]
	global_load_dwordx4 v[140:143], v178, s[98:99]
	global_load_dwordx4 v[148:151], v176, s[100:101]
	s_add_u32 s98, s98, s96
	s_addc_u32 s99, s99, s97
	s_add_u32 s100, s100, 0x80
	s_addc_u32 s101, s101, 0
	s_lshr_b32 s20, s88, 6
	s_add_i32 s20, s20, 1
	s_min_i32 s20, s20, s2
	s_mov_b32 s3, 0
	s_waitcnt lgkmcnt(0)
	s_barrier
	v_add_u32_e32 v206, v169, v0
	ds_read_b128 v[96:99], v206
	ds_read_b128 v[104:107], v206 offset:6656
	ds_read_b128 v[100:103], v206 offset:32
	ds_read_b128 v[108:111], v206 offset:6688
	ds_read_b128 v[112:115], v206 offset:64
	ds_read_b128 v[120:123], v206 offset:6720
	ds_read_b128 v[116:119], v206 offset:96
	ds_read_b128 v[124:127], v206 offset:6752
	s_waitcnt lgkmcnt(4)
	v_mfma_f32_32x32x16_bf16 v[64:79], v[96:99], v[2:5], v[48:63]
	v_mfma_f32_32x32x16_bf16 v[80:95], v[104:107], v[2:5], v[48:63]
	v_mfma_f32_32x32x16_bf16 v[64:79], v[100:103], v[6:9], v[64:79]
	v_mfma_f32_32x32x16_bf16 v[80:95], v[108:111], v[6:9], v[80:95]
	ds_read_b128 v[96:99], v206 offset:128
	ds_read_b128 v[104:107], v206 offset:6784
	ds_read_b128 v[100:103], v206 offset:160
	ds_read_b128 v[108:111], v206 offset:6816
	s_waitcnt lgkmcnt(4)
	v_mfma_f32_32x32x16_bf16 v[64:79], v[112:115], v[10:13], v[64:79]
	v_mfma_f32_32x32x16_bf16 v[80:95], v[120:123], v[10:13], v[80:95]
	v_mfma_f32_32x32x16_bf16 v[64:79], v[116:119], v[128:131], v[64:79]
	v_mfma_f32_32x32x16_bf16 v[80:95], v[124:127], v[128:131], v[80:95]
	s_waitcnt lgkmcnt(0)
	v_mfma_f32_32x32x16_bf16 v[64:79], v[96:99], v[132:135], v[64:79]
	v_mfma_f32_32x32x16_bf16 v[80:95], v[104:107], v[132:135], v[80:95]
	v_mfma_f32_32x32x16_bf16 v[64:79], v[100:103], v[136:139], v[64:79]
	v_mfma_f32_32x32x16_bf16 v[80:95], v[108:111], v[136:139], v[80:95]
; #define LAS __attribute__((address_space(3)))
; template <int DQK, int DV, int FLAGS, int qp, int kp, int vts, int op> ...
;     ...
;             for (int c = 0; c < ND0 / 2; ++c) {
;                 if (c + 1 < ND0 / 2) {
; #pragma unroll
;                     for (int i = 0; i < 2; ++i) { kf[(c + 1) & 1][2 * i] = *(const LAS bf16x8*)(kb + (2 * c + 2 + i) * 32); kf[(c + 1) & 1][2 * i + 1] = *(const LAS bf16x8*)(kb + 32 * KROW + (2 * c + 2 + i) * 32); }
;                 }
; #pragma unroll
;                 for (int i = 0; i < 2; ++i) {
;                     p0 = __builtin_amdgcn_mfma_f32_32x32x16_bf16(kf[c & 1][2 * i], qr[2 * c + i], p0, 0, 0, 0);
;                     p1 = __builtin_amdgcn_mfma_f32_32x32x16_bf16(kf[c & 1][2 * i + 1], qr[2 * c + i], p1, 0, 0, 0);
;                 }
;                 __builtin_amdgcn_sched_barrier(0);
;             }
;             if (more) ATT_GLOAD((FLAGS & AF_REV) ? t - 1 : t + 1);
;     ...
;             f32x2 rs2 = {0.f, 0.f};
; #pragma unroll
;             for (int r = 0; r < 16; ++r) { p0[r] = __builtin_amdgcn_exp2f(p0[r]); p1[r] = __builtin_amdgcn_exp2f(p1[r]); }
; #pragma unroll
;             for (int r = 0; r < 16; r += 2) { rs2 += (f32x2){p0[r], p0[r + 1]}; rs2 += (f32x2){p1[r], p1[r + 1]}; }
;             l += rs2.x + rs2.y;
;             bf16x8 pf[4];
;             pf[0] = pack_bf16x8(p0, 0); pf[1] = pack_bf16x8(p0, 8); pf[2] = pack_bf16x8(p1, 0); pf[3] = pack_bf16x8(p1, 8);
;             __builtin_amdgcn_sched_barrier(0);
; #pragma unroll
;             for (int d = 0; d < NDB; ++d) {
;                 if (d + 1 < NDB) {
; #pragma unroll
;                     for (int ks = 0; ks < 4; ++ks) vf[(d + 1) & 1][ks] = *(const LAS bf16x8*)(vb + (d + 1) * 32 * VROW + ks * 32);
;                 }
; #pragma unroll
;                 for (int ks = 0; ks < 4; ++ks) o[d] = __builtin_amdgcn_mfma_f32_32x32x16_bf16(vf[d & 1][ks], pf[ks], o[d], 0, 0, 0);
;                 __builtin_amdgcn_sched_barrier(0);
;             }
;         }
;         if (skip && more) ATT_GLOAD((FLAGS & AF_REV) ? t - 1 : t + 1);
;         if (more) ATT_LSTORE(cur ^ 1);
.Lq_top0:
	s_cmp_eq_u32 s3, 0
	s_cbranch_scc1 .Lq_gen0
	s_add_i32 s13, s3, 1
	s_cmp_ge_i32 s13, s20
	s_cbranch_scc1 .Lq_gen0
	s_add_i32 s12, s3, 1
	s_and_b32 s12, s12, 3
	s_mulk_i32 s12, 0x5800
	v_add3_u32 v206, s12, v169, v0
	ds_read_b128 v[96:99], v206
	ds_read_b128 v[104:107], v206 offset:6656
	ds_read_b128 v[100:103], v206 offset:32
	ds_read_b128 v[108:111], v206 offset:6688
	ds_read_b128 v[112:115], v206 offset:64
	ds_read_b128 v[120:123], v206 offset:6720
	ds_read_b128 v[116:119], v206 offset:96
	ds_read_b128 v[124:127], v206 offset:6752
	s_and_b32 s16, s3, 3
	s_mulk_i32 s16, 0x5800
	v_add3_u32 v207, s16, v171, v0
	v_mfma_f32_32x32x16_bf16 v[32:47], v[152:155], v[214:217], v[32:47]
	v_exp_f32_e32 v64, v64
	v_exp_f32_e32 v65, v65
	v_mfma_f32_32x32x16_bf16 v[16:31], v[188:191], v[214:217], v[16:31]
	v_exp_f32_e32 v80, v80
	v_exp_f32_e32 v81, v81
	v_mov_b32_e32 v204, v64
	v_mov_b32_e32 v205, v65
	s_add_i32 s12, s3, 2
	s_and_b32 s16, s12, 3
	s_mulk_i32 s16, 0x5800
	v_add_u32_e32 v209, s16, v14
	s_waitcnt vmcnt(0)
	ds_write_b128 v209, v[140:143]
	v_mfma_f32_32x32x16_bf16 v[32:47], v[156:159], v[218:221], v[32:47]
	v_exp_f32_e32 v66, v66
	v_exp_f32_e32 v67, v67
	v_add_f32_e32 v204, v80, v204
	v_add_f32_e32 v205, v81, v205
	v_add_u32_e32 v210, s16, v174
	ds_write_b128 v210, v[148:151] offset:13312
	v_mfma_f32_32x32x16_bf16 v[16:31], v[192:195], v[218:221], v[16:31]
	v_exp_f32_e32 v82, v82
	v_exp_f32_e32 v83, v83
	v_add_f32_e32 v204, v66, v204
	v_add_f32_e32 v205, v67, v205
	v_add_u32_e32 v211, s16, v172
	s_and_saveexec_b64 s[14:15], s[10:11]
	ds_write_b128 v211, v[144:147]
	s_or_b64 exec, exec, s[14:15]
	v_mfma_f32_32x32x16_bf16 v[32:47], v[160:163], v[222:225], v[32:47]
	v_exp_f32_e32 v68, v68
	v_exp_f32_e32 v69, v69
	v_add_f32_e32 v204, v82, v204
	v_add_f32_e32 v205, v83, v205
	s_add_i32 s12, s3, 3
	s_cmp_ge_i32 s12, s2
	s_cbranch_scc1 .Lq_ng0_s0
	s_and_saveexec_b64 s[14:15], s[10:11]
	global_load_dwordx4 v[144:147], v180, s[98:99]
	s_or_b64 exec, exec, s[14:15]
.Lq_ng0_s0:
	v_mfma_f32_32x32x16_bf16 v[16:31], v[196:199], v[222:225], v[16:31]
	v_exp_f32_e32 v84, v84
	v_exp_f32_e32 v85, v85
	v_add_f32_e32 v204, v68, v204
	v_add_f32_e32 v205, v69, v205
	s_add_i32 s12, s3, 3
	s_cmp_ge_i32 s12, s2
	s_cbranch_scc1 .Lq_ng1_s0
	global_load_dwordx4 v[140:143], v178, s[98:99]
.Lq_ng1_s0:
	v_mfma_f32_32x32x16_bf16 v[32:47], v[164:167], v[226:229], v[32:47]
	v_exp_f32_e32 v70, v70
	v_exp_f32_e32 v71, v71
	v_add_f32_e32 v204, v84, v204
	v_add_f32_e32 v205, v85, v205
	s_add_i32 s12, s3, 3
	s_cmp_ge_i32 s12, s2
	s_cbranch_scc1 .Lq_ng2_s0
	global_load_dwordx4 v[148:151], v176, s[100:101]
	s_add_u32 s98, s98, s96
	s_addc_u32 s99, s99, s97
	s_add_u32 s100, s100, 0x80
	s_addc_u32 s101, s101, 0

.Lq_noqk_p0:
.Lq_tail0:
	s_add_i32 s12, s3, 2
	s_cmp_ge_i32 s12, s2
	s_cbranch_scc1 .Lq_nols_p0
	s_and_b32 s16, s12, 3
	s_mulk_i32 s16, 0x5800
	s_waitcnt vmcnt(0)
	v_add_u32_e32 v209, s16, v14
	v_add_u32_e32 v210, s16, v174
	v_add_u32_e32 v211, s16, v172
	ds_write_b128 v209, v[140:143]
	ds_write_b128 v210, v[148:151] offset:13312
	s_and_saveexec_b64 s[14:15], s[10:11]
	ds_write_b128 v211, v[144:147]
	s_or_b64 exec, exec, s[14:15]
	s_add_i32 s12, s3, 3
	s_cmp_ge_i32 s12, s2
	s_cbranch_scc1 .Lq_nols_p0
	s_and_saveexec_b64 s[14:15], s[10:11]
	global_load_dwordx4 v[144:147], v180, s[98:99]
	s_or_b64 exec, exec, s[14:15]
	global_load_dwordx4 v[140:143], v178, s[98:99]
	global_load_dwordx4 v[148:151], v176, s[100:101]
	s_add_u32 s98, s98, s96
	s_addc_u32 s99, s99, s97
	s_add_u32 s100, s100, 0x80
	s_addc_u32 s101, s101, 0

; #define LAS __attribute__((address_space(3)))
; template <int DQK, int DV, int FLAGS, int qp, int kp, int vts, int op> ...
;     ...
;             for (int c = 0; c < ND0 / 2; ++c) {
;                 if (c + 1 < ND0 / 2) {
; #pragma unroll
;                     for (int i = 0; i < 2; ++i) { kf[(c + 1) & 1][2 * i] = *(const LAS bf16x8*)(kb + (2 * c + 2 + i) * 32); kf[(c + 1) & 1][2 * i + 1] = *(const LAS bf16x8*)(kb + 32 * KROW + (2 * c + 2 + i) * 32); }
;                 }
; #pragma unroll
;                 for (int i = 0; i < 2; ++i) {
;                     p0 = __builtin_amdgcn_mfma_f32_32x32x16_bf16(kf[c & 1][2 * i], qr[2 * c + i], p0, 0, 0, 0);
;                     p1 = __builtin_amdgcn_mfma_f32_32x32x16_bf16(kf[c & 1][2 * i + 1], qr[2 * c + i], p1, 0, 0, 0);
;                 }
;                 __builtin_amdgcn_sched_barrier(0);
;             }
;             if (more) ATT_GLOAD((FLAGS & AF_REV) ? t - 1 : t + 1);
;     ...
;             f32x2 rs2 = {0.f, 0.f};
; #pragma unroll
;             for (int r = 0; r < 16; ++r) { p0[r] = __builtin_amdgcn_exp2f(p0[r]); p1[r] = __builtin_amdgcn_exp2f(p1[r]); }
; #pragma unroll
;             for (int r = 0; r < 16; r += 2) { rs2 += (f32x2){p0[r], p0[r + 1]}; rs2 += (f32x2){p1[r], p1[r + 1]}; }
;             l += rs2.x + rs2.y;
;             bf16x8 pf[4];
;             pf[0] = pack_bf16x8(p0, 0); pf[1] = pack_bf16x8(p0, 8); pf[2] = pack_bf16x8(p1, 0); pf[3] = pack_bf16x8(p1, 8);
;             __builtin_amdgcn_sched_barrier(0);
; #pragma unroll
;             for (int d = 0; d < NDB; ++d) {
;                 if (d + 1 < NDB) {
; #pragma unroll
;                     for (int ks = 0; ks < 4; ++ks) vf[(d + 1) & 1][ks] = *(const LAS bf16x8*)(vb + (d + 1) * 32 * VROW + ks * 32);
;                 }
; #pragma unroll
;                 for (int ks = 0; ks < 4; ++ks) o[d] = __builtin_amdgcn_mfma_f32_32x32x16_bf16(vf[d & 1][ks], pf[ks], o[d], 0, 0, 0);
;                 __builtin_amdgcn_sched_barrier(0);
;             }
;         }
;         if (skip && more) ATT_GLOAD((FLAGS & AF_REV) ? t - 1 : t + 1);
;         if (more) ATT_LSTORE(cur ^ 1);
.Lq_top1:
	s_cmp_eq_u32 s3, 0
	s_cbranch_scc1 .Lq_gen1
	s_add_i32 s13, s3, 1
	s_cmp_ge_i32 s13, s20
	s_cbranch_scc1 .Lq_gen1
	s_add_i32 s12, s3, 1
	s_and_b32 s12, s12, 3
	s_mulk_i32 s12, 0x5800
	v_add3_u32 v206, s12, v169, v0
	ds_read_b128 v[96:99], v206
	ds_read_b128 v[104:107], v206 offset:6656
	ds_read_b128 v[100:103], v206 offset:32
	ds_read_b128 v[108:111], v206 offset:6688
	ds_read_b128 v[112:115], v206 offset:64
	ds_read_b128 v[120:123], v206 offset:6720
	ds_read_b128 v[116:119], v206 offset:96
	ds_read_b128 v[124:127], v206 offset:6752
	s_and_b32 s16, s3, 3
	s_mulk_i32 s16, 0x5800
	v_add3_u32 v207, s16, v171, v0
	v_mfma_f32_32x32x16_bf16 v[32:47], v[152:155], v[64:67], v[32:47]
	v_exp_f32_e32 v214, v214
	v_exp_f32_e32 v215, v215
	v_mfma_f32_32x32x16_bf16 v[16:31], v[188:191], v[64:67], v[16:31]
	v_exp_f32_e32 v230, v230
	v_exp_f32_e32 v231, v231
	v_mov_b32_e32 v204, v214
	v_mov_b32_e32 v205, v215
	s_add_i32 s12, s3, 2
	s_and_b32 s16, s12, 3
	s_mulk_i32 s16, 0x5800
	v_add_u32_e32 v209, s16, v14
	s_waitcnt vmcnt(0)
	ds_write_b128 v209, v[140:143]
	v_mfma_f32_32x32x16_bf16 v[32:47], v[156:159], v[68:71], v[32:47]
	v_exp_f32_e32 v216, v216
	v_exp_f32_e32 v217, v217
	v_add_f32_e32 v204, v230, v204
	v_add_f32_e32 v205, v231, v205
	v_add_u32_e32 v210, s16, v174
	ds_write_b128 v210, v[148:151] offset:13312
	v_mfma_f32_32x32x16_bf16 v[16:31], v[192:195], v[68:71], v[16:31]
	v_exp_f32_e32 v232, v232
	v_exp_f32_e32 v233, v233
	v_add_f32_e32 v204, v216, v204
	v_add_f32_e32 v205, v217, v205
	v_add_u32_e32 v211, s16, v172
	s_and_saveexec_b64 s[14:15], s[10:11]
	ds_write_b128 v211, v[144:147]
	s_or_b64 exec, exec, s[14:15]
	v_mfma_f32_32x32x16_bf16 v[32:47], v[160:163], v[72:75], v[32:47]
	v_exp_f32_e32 v218, v218
	v_exp_f32_e32 v219, v219
	v_add_f32_e32 v204, v232, v204
	v_add_f32_e32 v205, v233, v205
	s_add_i32 s12, s3, 3
	s_cmp_ge_i32 s12, s2
	s_cbranch_scc1 .Lq_ng0_s1
	s_and_saveexec_b64 s[14:15], s[10:11]
	global_load_dwordx4 v[144:147], v180, s[98:99]
	s_or_b64 exec, exec, s[14:15]
.Lq_ng0_s1:
	v_mfma_f32_32x32x16_bf16 v[16:31], v[196:199], v[72:75], v[16:31]
	v_exp_f32_e32 v234, v234
	v_exp_f32_e32 v235, v235
	v_add_f32_e32 v204, v218, v204
	v_add_f32_e32 v205, v219, v205
	s_add_i32 s12, s3, 3
	s_cmp_ge_i32 s12, s2
	s_cbranch_scc1 .Lq_ng1_s1
	global_load_dwordx4 v[140:143], v178, s[98:99]
.Lq_ng1_s1:
	v_mfma_f32_32x32x16_bf16 v[32:47], v[164:167], v[76:79], v[32:47]
	v_exp_f32_e32 v220, v220
	v_exp_f32_e32 v221, v221
	v_add_f32_e32 v204, v234, v204
	v_add_f32_e32 v205, v235, v205
	s_add_i32 s12, s3, 3
	s_cmp_ge_i32 s12, s2
	s_cbranch_scc1 .Lq_ng2_s1
	global_load_dwordx4 v[148:151], v176, s[100:101]
	s_add_u32 s98, s98, s96
	s_addc_u32 s99, s99, s97
	s_add_u32 s100, s100, 0x80
	s_addc_u32 s101, s101, 0

; template <int DQK, int DV, int FLAGS, int qp, int kp, int vts, int op> ...
;     ...
;     u32x4 kreg[KPT], vreg[VPT];
;     unsigned kgo[KPT], vgo[VPT], klo[KPT], vlo[VPT];
; #pragma unroll
;     for (int i = 0; i < KPT; ++i) { const int c = tid + i * NTHREADS; const int row = c / KC, cc = c % KC; kgo[i] = (unsigned)(row * kp + cc * 8) * 2u; klo[i] = (unsigned)(row * KROW + cc * 16); }
; #pragma unroll
;     for (int i = 0; i < VPT; ++i) { const int c = tid + i * NTHREADS; const int d = c >> 3, cc = c & 7; vgo[i] = (unsigned)(d * vts + cc * 8) * 2u; vlo[i] = (unsigned)(KT_BYTES + d * VROW + cc * 16); }
;     ...
;     ATT_GLOAD((FLAGS & AF_REV) ? kt_hi - 1 : kt_lo); ATT_LSTORE(0);
;     __syncthreads();
;     bool started = false;
;     const int prow = (r32 & ~12) | ((r32 & 4) << 1) | ((r32 & 8) >> 1);
;     const int ntile = kt_hi - kt_lo;
;     for (int it = 0; it < ntile; ++it) {
;         const int t = (FLAGS & AF_REV) ? kt_hi - 1 - it : kt_lo + it;
;         const int cur = it & 1;
;         const bool more = (it + 1 < ntile);
;         const int kv0 = t * 64;
;         bool skip = false;
;         if (FLAGS & AF_CAUSAL) skip = skip || (kv0 > qmax_w);
;         if (FLAGS & AF_WINDOW) skip = skip || (kv0 + 63 < qmin_w - (SWA_W - 1));
;         if (!skip) {
;             const LAS unsigned char* kb = lds + cur * BUF + prow * KROW + 16 * hi;
;             const LAS unsigned char* vb = lds + cur * BUF + KT_BYTES + r32 * VROW + 16 * hi;
;             f32x16 p0, p1;
;             bf16x8 kf[2][4];
; #pragma unroll
;             for (int i = 0; i < 2; ++i) { kf[0][2 * i] = *(const LAS bf16x8*)(kb + i * 32); kf[0][2 * i + 1] = *(const LAS bf16x8*)(kb + 32 * KROW + i * 32); }
;             const int nrel = qpos - kv0 - 8 * hi;
;             if (FLAGS & AF_ALIBI) { const float ab = -slope2 * (float)nrel - ((FLAGS & AF_ROBUST) ? 0.f : m);
; #pragma unroll
;                 for (int r = 0; r < 16; ++r) { const float c = (float)(16 * (r >> 3) + (r & 7)); p0[r] = __builtin_fmaf(slope2, c, ab); p1[r] = __builtin_fmaf(slope2, c + 32.f, ab); }
;             } else if (FLAGS & AF_ROBUST) {
; #pragma unroll
;                 for (int r = 0; r < 16; ++r) { p0[r] = 0.f; p1[r] = 0.f; }
;             } else { p0 = negm; p1 = negm; }
;             __builtin_amdgcn_sched_barrier(0);
; #pragma unroll
;             for (int c = 0; c < ND0 / 2; ++c) {
;                 if (c + 1 < ND0 / 2) {
.LBB0_933:
	s_andn2_b64 vcc, exec, s[8:9]
	v_lshlrev_b32_e32 v198, 3, v17
	s_cbranch_vccnz .LBB0_923
	v_and_b32_e32 v18, 31, v15
	v_and_b32_e32 v19, 19, v15
	v_lshlrev_b32_e32 v20, 1, v15
	v_lshrrev_b32_e32 v15, 1, v15
	s_and_b32 s8, s2, 0xffffffe0
	v_readlane_b32 s12, v255, 39
	v_and_b32_e32 v20, 8, v20
	v_and_b32_e32 v15, 4, v15
	v_mov_b32_e32 v17, v1
	s_add_i32 s20, s8, s12
	v_or3_b32 v15, v19, v20, v15
	s_addk_i32 s8, 0xff40
	v_mov_b32_e32 v64, v1
	v_mov_b32_e32 v65, v1
	v_mul_u32_u24_e32 v201, 0x90, v15
	v_mul_u32_u24_e32 v203, 0x90, v18
	v_lshl_add_u64 v[206:207], s[6:7], 0, v[16:17]
	v_add_u32_e32 v15, s8, v18
	v_mov_b32_e32 v66, v1
	v_mov_b32_e32 v67, v1
	v_mov_b32_e32 v68, v1
	v_mov_b32_e32 v69, v1
	v_mov_b32_e32 v70, v1
	v_mov_b32_e32 v71, v1
	v_mov_b32_e32 v72, v1
	v_mov_b32_e32 v73, v1
	v_mov_b32_e32 v74, v1
	v_mov_b32_e32 v75, v1
	v_mov_b32_e32 v76, v1
	v_mov_b32_e32 v77, v1
	v_mov_b32_e32 v78, v1
	v_mov_b32_e32 v79, v1
	v_mov_b64_e32 v[48:49], v[64:65]
	v_mov_b64_e32 v[32:33], v[64:65]
	v_mov_b64_e32 v[16:17], v[64:65]
	v_mov_b32_e32 v197, v1
	s_or_b32 s21, s20, 31
	s_add_i32 s2, s3, 0xff
	s_addk_i32 s3, 0x100
	v_mov_b32_e32 v208, v14
	v_mov_b32_e32 v209, v14
	v_mov_b32_e32 v210, v14
	v_mov_b32_e32 v211, v14
	s_sub_i32 s34, 0xfe, s11
	v_sub_u32_e32 v205, v15, v198
	s_sub_i32 s22, 0x3fff, s10
	s_mov_b32 s23, 0
	s_mov_b64 s[36:37], 0
	v_mov_b32_e32 v222, 0
	v_mov_b64_e32 v[50:51], v[66:67]
	v_mov_b64_e32 v[52:53], v[68:69]
	v_mov_b64_e32 v[54:55], v[70:71]
	v_mov_b64_e32 v[56:57], v[72:73]
	v_mov_b64_e32 v[58:59], v[74:75]
	v_mov_b64_e32 v[60:61], v[76:77]
	v_mov_b64_e32 v[62:63], v[78:79]
	v_mov_b64_e32 v[34:35], v[66:67]
	v_mov_b64_e32 v[36:37], v[68:69]
	v_mov_b64_e32 v[38:39], v[70:71]
	v_mov_b64_e32 v[40:41], v[72:73]
	v_mov_b64_e32 v[42:43], v[74:75]
	v_mov_b64_e32 v[44:45], v[76:77]
	v_mov_b64_e32 v[46:47], v[78:79]
	v_mov_b64_e32 v[18:19], v[66:67]
	v_mov_b64_e32 v[20:21], v[68:69]
	v_mov_b64_e32 v[22:23], v[70:71]
	v_mov_b64_e32 v[24:25], v[72:73]
	v_mov_b64_e32 v[26:27], v[74:75]
	v_mov_b64_e32 v[28:29], v[76:77]
	v_mov_b64_e32 v[30:31], v[78:79]
	v_mov_b32_e32 v199, 0
	v_readlane_b32 s13, v255, 40
	s_andn2_b64 vcc, exec, s[40:41]
	s_cbranch_vccnz .Ld_fallback
	v_readfirstlane_b32 s100, v206
	v_readfirstlane_b32 s101, v207
	s_nop 1
	v_subrev_u32_e32 v243, s100, v206
	s_add_i32 s34, s34, -1
	s_waitcnt vmcnt(0)
	v_add_u32_e32 v248, 0x6c00, v204
	v_add_u32_e32 v249, 0x6c00, v200
	v_add_u32_e32 v250, 0x6c00, v202
	ds_write_b128 v248, v[224:227]
	ds_write_b128 v249, v[228:231] offset:9216
	ds_write_b128 v250, v[232:235] offset:9216
	s_ashr_i32 s35, s34, 31
	s_lshl_b64 s[6:7], s[34:35], 17
	s_lshl_b64 s[10:11], s[34:35], 7
	s_add_u32 s10, s18, s10
	s_addc_u32 s11, s19, s11
	s_add_u32 s6, s6, s100
	s_addc_u32 s7, s7, s101
	global_load_dwordx4 v[148:151], v243, s[6:7]
	global_load_dwordx4 v[152:155], v0, s[10:11]
	global_load_dwordx4 v[156:159], v196, s[10:11]
	s_add_i32 s34, s34, -1
	s_mov_b32 s8, 0x42000000
	s_mov_b32 s9, 0x42040000
	s_sub_i32 s24, s22, s21
	s_ashr_i32 s24, s24, 6
	s_max_i32 s24, s24, 0
	s_waitcnt lgkmcnt(0)
	s_barrier
	s_cmp_lg_u32 s24, 0
	s_cbranch_scc1 .Ld_noqk0
	v_add_u32_e32 v244, v201, v194
	ds_read_b128 v[160:163], v244 offset:0
	ds_read_b128 v[164:167], v244 offset:32
	ds_read_b128 v[168:171], v244 offset:64
	ds_read_b128 v[172:175], v244 offset:96
	ds_read_b128 v[224:227], v244 offset:4608
	ds_read_b128 v[228:231], v244 offset:4640
	ds_read_b128 v[232:235], v244 offset:4672
	ds_read_b128 v[236:239], v244 offset:4704
	v_cvt_f32_i32_e32 v246, v205
	v_fma_f32 v242, -v14, v246, -v222
	v_mov_b32_e32 v80, v242
	v_add_f32_e32 v81, v14, v242
	v_fma_f32 v82, v14, s62, v242
	v_fma_f32 v83, v14, s63, v242
	v_fma_f32 v84, v14, s64, v242
	v_fma_f32 v85, v14, s65, v242
	v_fma_f32 v86, v14, s66, v242
	v_fma_f32 v87, v14, s67, v242
	v_fma_f32 v88, v14, s68, v242
	v_fma_f32 v89, v14, s69, v242
	v_fma_f32 v90, v14, s70, v242
	v_fma_f32 v91, v14, s71, v242
	v_fma_f32 v92, v14, s72, v242
	v_fma_f32 v93, v14, s73, v242
	v_fma_f32 v94, v14, s76, v242
	v_fma_f32 v95, v14, s77, v242
	v_fma_f32 v96, v14, s8, v242
	v_fma_f32 v97, v14, s9, v242
	v_fma_f32 v98, v14, s96, v242
	v_fma_f32 v99, v14, s97, v242
	v_fma_f32 v100, v14, s94, v242
	v_fma_f32 v101, v14, s95, v242
	v_fma_f32 v102, v14, s92, v242
	v_fma_f32 v103, v14, s93, v242
	v_fma_f32 v104, v14, s90, v242
	v_fma_f32 v105, v14, s91, v242
	v_fma_f32 v106, v14, s88, v242
	v_fma_f32 v107, v14, s89, v242
	v_fma_f32 v108, v14, s86, v242
	v_fma_f32 v109, v14, s87, v242
	v_fma_f32 v110, v14, s78, v242
	v_fma_f32 v111, v14, s79, v242
	s_waitcnt lgkmcnt(0)
	v_mfma_f32_32x32x16_bf16 v[80:95], v[160:163], v[2:5], v[80:95]
	v_mfma_f32_32x32x16_bf16 v[96:111], v[224:227], v[2:5], v[96:111]
	v_mfma_f32_32x32x16_bf16 v[80:95], v[164:167], v[6:9], v[80:95]
	v_mfma_f32_32x32x16_bf16 v[96:111], v[228:231], v[6:9], v[96:111]
	v_mfma_f32_32x32x16_bf16 v[80:95], v[168:171], v[10:13], v[80:95]
	v_mfma_f32_32x32x16_bf16 v[96:111], v[232:235], v[10:13], v[96:111]
	v_mfma_f32_32x32x16_bf16 v[80:95], v[172:175], v[144:147], v[80:95]
	v_mfma_f32_32x32x16_bf16 v[96:111], v[236:239], v[144:147], v[96:111]
; #define LAS __attribute__((address_space(3)))
; #define ATT_LSTORE(buf) do { LAS unsigned char* b_ = lds + (buf) * BUF; \
;         _Pragma("unroll") for (int i = 0; i < KPT; ++i) { if (KCH % NTHREADS == 0 || tid + i * NTHREADS < KCH) *(LAS u32x4*)(b_ + klo[i]) = kreg[i]; } \
;         _Pragma("unroll") for (int i = 0; i < VPT; ++i) *(LAS u32x4*)(b_ + vlo[i]) = vreg[i]; } while (0)
; template <int DQK, int DV, int FLAGS, int qp, int kp, int vts, int op> ...
;     ...
;             f32x2 rs2 = {0.f, 0.f};
; #pragma unroll
;             for (int r = 0; r < 16; ++r) { p0[r] = __builtin_amdgcn_exp2f(p0[r]); p1[r] = __builtin_amdgcn_exp2f(p1[r]); }
; #pragma unroll
;             for (int r = 0; r < 16; r += 2) { rs2 += (f32x2){p0[r], p0[r + 1]}; rs2 += (f32x2){p1[r], p1[r + 1]}; }
;             l += rs2.x + rs2.y;
;             bf16x8 pf[4];
;             pf[0] = pack_bf16x8(p0, 0); pf[1] = pack_bf16x8(p0, 8); pf[2] = pack_bf16x8(p1, 0); pf[3] = pack_bf16x8(p1, 8);
;             __builtin_amdgcn_sched_barrier(0);
; #pragma unroll
;             for (int d = 0; d < NDB; ++d) {
;                 if (d + 1 < NDB) {
; #pragma unroll
;                     for (int ks = 0; ks < 4; ++ks) vf[(d + 1) & 1][ks] = *(const LAS bf16x8*)(vb + (d + 1) * 32 * VROW + ks * 32);
;                 }
; #pragma unroll
;                 for (int ks = 0; ks < 4; ++ks) o[d] = __builtin_amdgcn_mfma_f32_32x32x16_bf16(vf[d & 1][ks], pf[ks], o[d], 0, 0, 0);
;                 __builtin_amdgcn_sched_barrier(0);
;             }
;         }
;         if (skip && more) ATT_GLOAD((FLAGS & AF_REV) ? t - 1 : t + 1);
;         if (more) ATT_LSTORE(cur ^ 1);
.Ld_noqk0:
.Ld_top0:
	s_cmp_le_i32 s23, s24
	s_cbranch_scc1 .Ld_gen0
	s_add_i32 s13, s23, 1
	s_cmp_ge_i32 s13, s3
	s_cbranch_scc1 .Ld_gen0
	s_add_i32 s12, s23, -1
	s_and_b32 s12, s12, 3
	s_mulk_i32 s12, 0x6c00
	v_add3_u32 v245, s12, v203, v194
	ds_read_b128 v[224:227], v245 offset:13824
	ds_read_b128 v[228:231], v245 offset:13856
	ds_read_b128 v[232:235], v245 offset:13888
	ds_read_b128 v[236:239], v245 offset:13920
	s_add_i32 s12, s23, 1
	s_and_b32 s12, s12, 3
	s_mulk_i32 s12, 0x6c00
	v_add3_u32 v244, s12, v201, v194
	s_and_b32 s12, s23, 3
	s_mulk_i32 s12, 0x6c00
	v_add3_u32 v251, s12, v203, v194
	v_mfma_f32_32x32x16_bf16 v[64:79], v[160:163], v[112:115], v[64:79]
	v_exp_f32_e32 v80, v80
	v_exp_f32_e32 v81, v81
	v_exp_f32_e32 v96, v96
	v_exp_f32_e32 v97, v97
	v_add_u32_e32 v246, 64, v205
	v_mov_b32_e32 v240, v80
	v_mfma_f32_32x32x16_bf16 v[64:79], v[164:167], v[116:119], v[64:79]
	v_mov_b32_e32 v241, v81
	v_exp_f32_e32 v82, v82
	v_exp_f32_e32 v83, v83
	v_cvt_f32_i32_e32 v246, v246
	v_add_f32_e32 v240, v96, v240
	v_add_f32_e32 v241, v97, v241
	v_mfma_f32_32x32x16_bf16 v[64:79], v[168:171], v[120:123], v[64:79]
	v_exp_f32_e32 v98, v98
	v_exp_f32_e32 v99, v99
	v_fma_f32 v242, -v14, v246, -v222
	v_add_f32_e32 v240, v82, v240
	v_add_f32_e32 v241, v83, v241
	v_exp_f32_e32 v84, v84
	v_mfma_f32_32x32x16_bf16 v[64:79], v[172:175], v[124:127], v[64:79]
	v_exp_f32_e32 v85, v85
	v_fma_f32 v128, v14, s8, v242
	v_add_f32_e32 v240, v98, v240
	v_add_f32_e32 v241, v99, v241
	v_exp_f32_e32 v100, v100
	v_exp_f32_e32 v101, v101
	ds_read_b128 v[160:163], v245 offset:18432
	ds_read_b128 v[164:167], v245 offset:18464
	ds_read_b128 v[168:171], v245 offset:18496
	ds_read_b128 v[172:175], v245 offset:18528
	s_waitcnt lgkmcnt(4)
	v_mfma_f32_32x32x16_bf16 v[48:63], v[224:227], v[112:115], v[48:63]
	v_fma_f32 v129, v14, s9, v242
	v_add_f32_e32 v240, v84, v240
	v_add_f32_e32 v241, v85, v241
	v_exp_f32_e32 v86, v86
	v_exp_f32_e32 v87, v87
	v_fma_f32 v130, v14, s96, v242
	s_add_i32 s12, s23, 2
	s_and_b32 s13, s12, 3
	s_mulk_i32 s13, 0x6c00
	v_add_u32_e32 v248, s13, v204
	s_waitcnt vmcnt(0)
	ds_write_b128 v248, v[148:151]
	v_mfma_f32_32x32x16_bf16 v[48:63], v[228:231], v[116:119], v[48:63]
	v_add_f32_e32 v240, v100, v240
	v_add_f32_e32 v241, v101, v241
	v_exp_f32_e32 v102, v102
	v_exp_f32_e32 v103, v103
	v_fma_f32 v131, v14, s97, v242
	v_add_f32_e32 v240, v86, v240
	v_add_u32_e32 v249, s13, v200
	ds_write_b128 v249, v[152:155] offset:9216
	v_mfma_f32_32x32x16_bf16 v[48:63], v[232:235], v[120:123], v[48:63]
	v_add_f32_e32 v241, v87, v241
	v_exp_f32_e32 v88, v88
	v_exp_f32_e32 v89, v89
	v_fma_f32 v132, v14, s94, v242
	v_add_f32_e32 v240, v102, v240
	v_add_f32_e32 v241, v103, v241
	v_add_u32_e32 v250, s13, v202
	ds_write_b128 v250, v[156:159] offset:9216
	v_mfma_f32_32x32x16_bf16 v[48:63], v[236:239], v[124:127], v[48:63]
	v_exp_f32_e32 v104, v104
	v_exp_f32_e32 v105, v105
	v_fma_f32 v133, v14, s95, v242
	v_add_f32_e32 v240, v88, v240
	v_add_f32_e32 v241, v89, v241
	v_exp_f32_e32 v90, v90
	ds_read_b128 v[224:227], v245 offset:23040
	ds_read_b128 v[228:231], v245 offset:23072
	ds_read_b128 v[232:235], v245 offset:23104
	ds_read_b128 v[236:239], v245 offset:23136
	s_waitcnt lgkmcnt(4)
	v_mfma_f32_32x32x16_bf16 v[32:47], v[160:163], v[112:115], v[32:47]
	v_exp_f32_e32 v91, v91
	v_fma_f32 v134, v14, s92, v242
	v_add_f32_e32 v240, v104, v240
	v_add_f32_e32 v241, v105, v241
	v_exp_f32_e32 v106, v106
	v_exp_f32_e32 v107, v107
	v_mfma_f32_32x32x16_bf16 v[32:47], v[164:167], v[116:119], v[32:47]
	v_fma_f32 v135, v14, s93, v242
	v_add_f32_e32 v240, v90, v240
	v_add_f32_e32 v241, v91, v241
	v_exp_f32_e32 v92, v92
	v_exp_f32_e32 v93, v93
	v_fma_f32 v136, v14, s90, v242
	s_ashr_i32 s35, s34, 31
	s_lshl_b64 s[6:7], s[34:35], 17
	s_lshl_b64 s[10:11], s[34:35], 7
	s_add_u32 s10, s18, s10
	s_addc_u32 s11, s19, s11
	s_add_u32 s6, s6, s100
	s_addc_u32 s7, s7, s101
	global_load_dwordx4 v[148:151], v243, s[6:7]
	v_mfma_f32_32x32x16_bf16 v[32:47], v[168:171], v[120:123], v[32:47]
	v_add_f32_e32 v240, v106, v240
	v_add_f32_e32 v241, v107, v241
	v_exp_f32_e32 v108, v108
	v_exp_f32_e32 v109, v109
	v_fma_f32 v137, v14, s91, v242
	v_add_f32_e32 v240, v92, v240
	global_load_dwordx4 v[152:155], v0, s[10:11]
	v_mfma_f32_32x32x16_bf16 v[32:47], v[172:175], v[124:127], v[32:47]
	v_add_f32_e32 v241, v93, v241
	v_exp_f32_e32 v94, v94
	v_exp_f32_e32 v95, v95
	v_fma_f32 v138, v14, s88, v242
	v_add_f32_e32 v240, v108, v240
	v_add_f32_e32 v241, v109, v241
	global_load_dwordx4 v[156:159], v196, s[10:11]
	s_add_i32 s34, s34, -1
	ds_read_b128 v[160:163], v244 offset:4608
	ds_read_b128 v[164:167], v244 offset:4640
	ds_read_b128 v[168:171], v244 offset:4672
	ds_read_b128 v[172:175], v244 offset:4704
	s_waitcnt lgkmcnt(4)
; #define LAS __attribute__((address_space(3)))
; template <int DQK, int DV, int FLAGS, int qp, int kp, int vts, int op> ...
;     ...
;             if (FLAGS & AF_ALIBI) { const float ab = -slope2 * (float)nrel - ((FLAGS & AF_ROBUST) ? 0.f : m);
; #pragma unroll
;                 for (int r = 0; r < 16; ++r) { const float c = (float)(16 * (r >> 3) + (r & 7)); p0[r] = __builtin_fmaf(slope2, c, ab); p1[r] = __builtin_fmaf(slope2, c + 32.f, ab); }
;             } else if (FLAGS & AF_ROBUST) {
; #pragma unroll
;                 for (int r = 0; r < 16; ++r) { p0[r] = 0.f; p1[r] = 0.f; }
;             } else { p0 = negm; p1 = negm; }
;             __builtin_amdgcn_sched_barrier(0);
; #pragma unroll
;             for (int c = 0; c < ND0 / 2; ++c) {
;                 if (c + 1 < ND0 / 2) {
; #pragma unroll
;                     for (int i = 0; i < 2; ++i) { kf[(c + 1) & 1][2 * i] = *(const LAS bf16x8*)(kb + (2 * c + 2 + i) * 32); kf[(c + 1) & 1][2 * i + 1] = *(const LAS bf16x8*)(kb + 32 * KROW + (2 * c + 2 + i) * 32); }
;                 }
; #pragma unroll
;                 for (int i = 0; i < 2; ++i) {
;                     p0 = __builtin_amdgcn_mfma_f32_32x32x16_bf16(kf[c & 1][2 * i], qr[2 * c + i], p0, 0, 0, 0);
;                     p1 = __builtin_amdgcn_mfma_f32_32x32x16_bf16(kf[c & 1][2 * i + 1], qr[2 * c + i], p1, 0, 0, 0);
;                 }
;                 __builtin_amdgcn_sched_barrier(0);
;             }
;     ...
;             f32x2 rs2 = {0.f, 0.f};
; #pragma unroll
;             for (int r = 0; r < 16; ++r) { p0[r] = __builtin_amdgcn_exp2f(p0[r]); p1[r] = __builtin_amdgcn_exp2f(p1[r]); }
; #pragma unroll
;             for (int r = 0; r < 16; r += 2) { rs2 += (f32x2){p0[r], p0[r + 1]}; rs2 += (f32x2){p1[r], p1[r + 1]}; }
;             l += rs2.x + rs2.y;
;             bf16x8 pf[4];
;             pf[0] = pack_bf16x8(p0, 0); pf[1] = pack_bf16x8(p0, 8); pf[2] = pack_bf16x8(p1, 0); pf[3] = pack_bf16x8(p1, 8);
;             __builtin_amdgcn_sched_barrier(0);
; #pragma unroll
;             for (int d = 0; d < NDB; ++d) {
;                 if (d + 1 < NDB) {
; #pragma unroll
;                     for (int ks = 0; ks < 4; ++ks) vf[(d + 1) & 1][ks] = *(const LAS bf16x8*)(vb + (d + 1) * 32 * VROW + ks * 32);
;                 }
; #pragma unroll
;                 for (int ks = 0; ks < 4; ++ks) o[d] = __builtin_amdgcn_mfma_f32_32x32x16_bf16(vf[d & 1][ks], pf[ks], o[d], 0, 0, 0);
	v_mfma_f32_32x32x16_bf16 v[16:31], v[224:227], v[112:115], v[16:31]
	v_exp_f32_e32 v110, v110
	v_exp_f32_e32 v111, v111
	v_fma_f32 v139, v14, s89, v242
	v_add_f32_e32 v240, v94, v240
	v_add_f32_e32 v241, v95, v241
	v_fma_f32 v140, v14, s86, v242
	v_mfma_f32_32x32x16_bf16 v[16:31], v[228:231], v[116:119], v[16:31]
	v_fma_f32 v141, v14, s87, v242
	v_fma_f32 v142, v14, s78, v242
	v_fma_f32 v143, v14, s79, v242
	v_mfma_f32_32x32x16_bf16 v[16:31], v[232:235], v[120:123], v[16:31]
	v_mfma_f32_32x32x16_bf16 v[16:31], v[236:239], v[124:127], v[16:31]
	ds_read_b128 v[224:227], v244 offset:0
	ds_read_b128 v[228:231], v244 offset:32
	ds_read_b128 v[232:235], v244 offset:64
	ds_read_b128 v[236:239], v244 offset:96
	s_waitcnt lgkmcnt(4)
	v_mfma_f32_32x32x16_bf16 v[128:143], v[160:163], v[2:5], v[128:143]
	v_mov_b32_e32 v112, v242
	v_add_f32_e32 v113, v14, v242
	v_fma_f32 v114, v14, s62, v242
	v_fma_f32 v115, v14, s63, v242
	v_mfma_f32_32x32x16_bf16 v[128:143], v[164:167], v[6:9], v[128:143]
	v_fma_f32 v116, v14, s64, v242
	v_fma_f32 v117, v14, s65, v242
	v_fma_f32 v118, v14, s66, v242
	v_fma_f32 v119, v14, s67, v242
	v_mfma_f32_32x32x16_bf16 v[128:143], v[168:171], v[10:13], v[128:143]
	v_fma_f32 v120, v14, s68, v242
	v_fma_f32 v121, v14, s69, v242
	v_fma_f32 v122, v14, s70, v242
	v_fma_f32 v123, v14, s71, v242
	v_mfma_f32_32x32x16_bf16 v[128:143], v[172:175], v[144:147], v[128:143]
	v_fma_f32 v124, v14, s72, v242
	v_fma_f32 v125, v14, s73, v242
	v_fma_f32 v126, v14, s76, v242
	v_fma_f32 v127, v14, s77, v242
	ds_read_b128 v[160:163], v251 offset:9216
	ds_read_b128 v[164:167], v251 offset:9248
	ds_read_b128 v[168:171], v251 offset:9280
	ds_read_b128 v[172:175], v251 offset:9312
	s_waitcnt lgkmcnt(4)
	v_mfma_f32_32x32x16_bf16 v[112:127], v[224:227], v[2:5], v[112:127]
	s_nop 0
	v_add_f32_e32 v240, v110, v240
	v_add_f32_e32 v241, v111, v241
	v_cvt_pk_bf16_f32 v80, v80, v81
	v_cvt_pk_bf16_f32 v81, v82, v83
	v_cvt_pk_bf16_f32 v82, v84, v85
	v_mfma_f32_32x32x16_bf16 v[112:127], v[228:231], v[6:9], v[112:127]
	v_cvt_pk_bf16_f32 v83, v86, v87
	v_cvt_pk_bf16_f32 v84, v88, v89
	v_cvt_pk_bf16_f32 v85, v90, v91
	v_cvt_pk_bf16_f32 v86, v92, v93
	v_cvt_pk_bf16_f32 v87, v94, v95
	v_cvt_pk_bf16_f32 v88, v96, v97
	v_mfma_f32_32x32x16_bf16 v[112:127], v[232:235], v[10:13], v[112:127]
	v_cvt_pk_bf16_f32 v89, v98, v99
	v_cvt_pk_bf16_f32 v90, v100, v101
	v_cvt_pk_bf16_f32 v91, v102, v103
	v_cvt_pk_bf16_f32 v92, v104, v105
	v_cvt_pk_bf16_f32 v93, v106, v107
	v_cvt_pk_bf16_f32 v94, v108, v109
	v_mfma_f32_32x32x16_bf16 v[112:127], v[236:239], v[144:147], v[112:127]
	v_cvt_pk_bf16_f32 v95, v110, v111
	v_add_f32_e32 v247, v240, v241
	v_add_f32_e32 v199, v199, v247
	s_branch .Ld_tail0
.Ld_gen0:
	s_add_i32 s12, s23, 2
	s_cmp_ge_i32 s12, s3
	s_cbranch_scc1 .Ld_nols_p0
	s_and_b32 s13, s12, 3
	s_mulk_i32 s13, 0x6c00
	s_waitcnt vmcnt(0)
	v_add_u32_e32 v248, s13, v204
	v_add_u32_e32 v249, s13, v200
	v_add_u32_e32 v250, s13, v202
	ds_write_b128 v248, v[148:151]
	ds_write_b128 v249, v[152:155] offset:9216
	ds_write_b128 v250, v[156:159] offset:9216
	s_add_i32 s12, s23, 3
	s_cmp_ge_i32 s12, s3
	s_cbranch_scc1 .Ld_nols_p0
	s_ashr_i32 s35, s34, 31
	s_lshl_b64 s[6:7], s[34:35], 17
	s_lshl_b64 s[10:11], s[34:35], 7
	s_add_u32 s10, s18, s10
	s_addc_u32 s11, s19, s11
	s_add_u32 s6, s6, s100
	s_addc_u32 s7, s7, s101
	global_load_dwordx4 v[148:151], v243, s[6:7]
	global_load_dwordx4 v[152:155], v0, s[10:11]
	global_load_dwordx4 v[156:159], v196, s[10:11]
	s_add_i32 s34, s34, -1

; #define LAS __attribute__((address_space(3)))
; template <int DQK, int DV, int FLAGS, int qp, int kp, int vts, int op> ...
;     ...
;             if (FLAGS & AF_ALIBI) { const float ab = -slope2 * (float)nrel - ((FLAGS & AF_ROBUST) ? 0.f : m);
; #pragma unroll
;                 for (int r = 0; r < 16; ++r) { const float c = (float)(16 * (r >> 3) + (r & 7)); p0[r] = __builtin_fmaf(slope2, c, ab); p1[r] = __builtin_fmaf(slope2, c + 32.f, ab); }
;     ...
;             for (int d = 0; d < NDB; ++d) {
;                 if (d + 1 < NDB) {
; #pragma unroll
;                     for (int ks = 0; ks < 4; ++ks) vf[(d + 1) & 1][ks] = *(const LAS bf16x8*)(vb + (d + 1) * 32 * VROW + ks * 32);
;                 }
; #pragma unroll
;                 for (int ks = 0; ks < 4; ++ks) o[d] = __builtin_amdgcn_mfma_f32_32x32x16_bf16(vf[d & 1][ks], pf[ks], o[d], 0, 0, 0);
;                 __builtin_amdgcn_sched_barrier(0);
;             }
.Ld_top1:
	s_cmp_le_i32 s23, s24
	s_cbranch_scc1 .Ld_gen1
	s_add_i32 s13, s23, 1
	s_cmp_ge_i32 s13, s3
	s_cbranch_scc1 .Ld_gen1
	s_add_i32 s12, s23, -1
	s_and_b32 s12, s12, 3
	s_mulk_i32 s12, 0x6c00
	v_add3_u32 v245, s12, v203, v194
	ds_read_b128 v[224:227], v245 offset:13824
	ds_read_b128 v[228:231], v245 offset:13856
	ds_read_b128 v[232:235], v245 offset:13888
	ds_read_b128 v[236:239], v245 offset:13920
	s_add_i32 s12, s23, 1
	s_and_b32 s12, s12, 3
	s_mulk_i32 s12, 0x6c00
	v_add3_u32 v244, s12, v201, v194
	s_and_b32 s12, s23, 3
	s_mulk_i32 s12, 0x6c00
	v_add3_u32 v251, s12, v203, v194
	v_mfma_f32_32x32x16_bf16 v[64:79], v[160:163], v[80:83], v[64:79]
	v_exp_f32_e32 v112, v112
	v_exp_f32_e32 v113, v113
	v_exp_f32_e32 v128, v128
	v_exp_f32_e32 v129, v129
	v_add_u32_e32 v246, 64, v205
	v_mov_b32_e32 v240, v112
	v_mfma_f32_32x32x16_bf16 v[64:79], v[164:167], v[84:87], v[64:79]
	v_mov_b32_e32 v241, v113
	v_exp_f32_e32 v114, v114
	v_exp_f32_e32 v115, v115
	v_cvt_f32_i32_e32 v246, v246
	v_add_f32_e32 v240, v128, v240
	v_add_f32_e32 v241, v129, v241
	v_mfma_f32_32x32x16_bf16 v[64:79], v[168:171], v[88:91], v[64:79]
	v_exp_f32_e32 v130, v130
	v_exp_f32_e32 v131, v131
	v_fma_f32 v242, -v14, v246, -v222
	v_add_f32_e32 v240, v114, v240
	v_add_f32_e32 v241, v115, v241
	v_exp_f32_e32 v116, v116
	v_mfma_f32_32x32x16_bf16 v[64:79], v[172:175], v[92:95], v[64:79]
	v_exp_f32_e32 v117, v117
	v_fma_f32 v96, v14, s8, v242
	v_add_f32_e32 v240, v130, v240
	v_add_f32_e32 v241, v131, v241
	v_exp_f32_e32 v132, v132
	v_exp_f32_e32 v133, v133
	ds_read_b128 v[160:163], v245 offset:18432
	ds_read_b128 v[164:167], v245 offset:18464
	ds_read_b128 v[168:171], v245 offset:18496
	ds_read_b128 v[172:175], v245 offset:18528
	s_waitcnt lgkmcnt(4)
	v_mfma_f32_32x32x16_bf16 v[48:63], v[224:227], v[80:83], v[48:63]
	v_fma_f32 v97, v14, s9, v242
	v_add_f32_e32 v240, v116, v240
	v_add_f32_e32 v241, v117, v241
	v_exp_f32_e32 v118, v118
	v_exp_f32_e32 v119, v119
	v_fma_f32 v98, v14, s96, v242
	s_add_i32 s12, s23, 2
	s_and_b32 s13, s12, 3
	s_mulk_i32 s13, 0x6c00
	v_add_u32_e32 v248, s13, v204
	s_waitcnt vmcnt(0)
	ds_write_b128 v248, v[148:151]
	v_mfma_f32_32x32x16_bf16 v[48:63], v[228:231], v[84:87], v[48:63]
	v_add_f32_e32 v240, v132, v240
	v_add_f32_e32 v241, v133, v241
	v_exp_f32_e32 v134, v134
	v_exp_f32_e32 v135, v135
	v_fma_f32 v99, v14, s97, v242
	v_add_f32_e32 v240, v118, v240
	v_add_u32_e32 v249, s13, v200
	ds_write_b128 v249, v[152:155] offset:9216
	v_mfma_f32_32x32x16_bf16 v[48:63], v[232:235], v[88:91], v[48:63]
	v_add_f32_e32 v241, v119, v241
	v_exp_f32_e32 v120, v120
	v_exp_f32_e32 v121, v121
	v_fma_f32 v100, v14, s94, v242
	v_add_f32_e32 v240, v134, v240
	v_add_f32_e32 v241, v135, v241
	v_add_u32_e32 v250, s13, v202
	ds_write_b128 v250, v[156:159] offset:9216
	v_mfma_f32_32x32x16_bf16 v[48:63], v[236:239], v[92:95], v[48:63]
	v_exp_f32_e32 v136, v136
	v_exp_f32_e32 v137, v137
	v_fma_f32 v101, v14, s95, v242
	v_add_f32_e32 v240, v120, v240
	v_add_f32_e32 v241, v121, v241
	v_exp_f32_e32 v122, v122
	ds_read_b128 v[224:227], v245 offset:23040
	ds_read_b128 v[228:231], v245 offset:23072
	ds_read_b128 v[232:235], v245 offset:23104
	ds_read_b128 v[236:239], v245 offset:23136
	s_waitcnt lgkmcnt(4)
; #define LAS __attribute__((address_space(3)))
; template <int DQK, int DV, int FLAGS, int qp, int kp, int vts, int op> ...
;     ...
;             if (FLAGS & AF_ALIBI) { const float ab = -slope2 * (float)nrel - ((FLAGS & AF_ROBUST) ? 0.f : m);
; #pragma unroll
;                 for (int r = 0; r < 16; ++r) { const float c = (float)(16 * (r >> 3) + (r & 7)); p0[r] = __builtin_fmaf(slope2, c, ab); p1[r] = __builtin_fmaf(slope2, c + 32.f, ab); }
;             } else if (FLAGS & AF_ROBUST) {
; #pragma unroll
;                 for (int r = 0; r < 16; ++r) { p0[r] = 0.f; p1[r] = 0.f; }
;             } else { p0 = negm; p1 = negm; }
;             __builtin_amdgcn_sched_barrier(0);
; #pragma unroll
;             for (int c = 0; c < ND0 / 2; ++c) {
;                 if (c + 1 < ND0 / 2) {
; #pragma unroll
;                     for (int i = 0; i < 2; ++i) { kf[(c + 1) & 1][2 * i] = *(const LAS bf16x8*)(kb + (2 * c + 2 + i) * 32); kf[(c + 1) & 1][2 * i + 1] = *(const LAS bf16x8*)(kb + 32 * KROW + (2 * c + 2 + i) * 32); }
;                 }
; #pragma unroll
;                 for (int i = 0; i < 2; ++i) {
;                     p0 = __builtin_amdgcn_mfma_f32_32x32x16_bf16(kf[c & 1][2 * i], qr[2 * c + i], p0, 0, 0, 0);
;                     p1 = __builtin_amdgcn_mfma_f32_32x32x16_bf16(kf[c & 1][2 * i + 1], qr[2 * c + i], p1, 0, 0, 0);
;                 }
;                 __builtin_amdgcn_sched_barrier(0);
;             }
;     ...
;             f32x2 rs2 = {0.f, 0.f};
; #pragma unroll
;             for (int r = 0; r < 16; ++r) { p0[r] = __builtin_amdgcn_exp2f(p0[r]); p1[r] = __builtin_amdgcn_exp2f(p1[r]); }
; #pragma unroll
;             for (int r = 0; r < 16; r += 2) { rs2 += (f32x2){p0[r], p0[r + 1]}; rs2 += (f32x2){p1[r], p1[r + 1]}; }
;             l += rs2.x + rs2.y;
;             bf16x8 pf[4];
;             pf[0] = pack_bf16x8(p0, 0); pf[1] = pack_bf16x8(p0, 8); pf[2] = pack_bf16x8(p1, 0); pf[3] = pack_bf16x8(p1, 8);
;             __builtin_amdgcn_sched_barrier(0);
; #pragma unroll
;             for (int d = 0; d < NDB; ++d) {
;                 if (d + 1 < NDB) {
; #pragma unroll
;                     for (int ks = 0; ks < 4; ++ks) vf[(d + 1) & 1][ks] = *(const LAS bf16x8*)(vb + (d + 1) * 32 * VROW + ks * 32);
;                 }
; #pragma unroll
;                 for (int ks = 0; ks < 4; ++ks) o[d] = __builtin_amdgcn_mfma_f32_32x32x16_bf16(vf[d & 1][ks], pf[ks], o[d], 0, 0, 0);
	v_mfma_f32_32x32x16_bf16 v[32:47], v[160:163], v[80:83], v[32:47]
	v_exp_f32_e32 v123, v123
	v_fma_f32 v102, v14, s92, v242
	v_add_f32_e32 v240, v136, v240
	v_add_f32_e32 v241, v137, v241
	v_exp_f32_e32 v138, v138
	v_exp_f32_e32 v139, v139
	v_mfma_f32_32x32x16_bf16 v[32:47], v[164:167], v[84:87], v[32:47]
	v_fma_f32 v103, v14, s93, v242
	v_add_f32_e32 v240, v122, v240
	v_add_f32_e32 v241, v123, v241
	v_exp_f32_e32 v124, v124
	v_exp_f32_e32 v125, v125
	v_fma_f32 v104, v14, s90, v242
	s_ashr_i32 s35, s34, 31
	s_lshl_b64 s[6:7], s[34:35], 17
	s_lshl_b64 s[10:11], s[34:35], 7
	s_add_u32 s10, s18, s10
	s_addc_u32 s11, s19, s11
	s_add_u32 s6, s6, s100
	s_addc_u32 s7, s7, s101
	global_load_dwordx4 v[148:151], v243, s[6:7]
	v_mfma_f32_32x32x16_bf16 v[32:47], v[168:171], v[88:91], v[32:47]
	v_add_f32_e32 v240, v138, v240
	v_add_f32_e32 v241, v139, v241
	v_exp_f32_e32 v140, v140
	v_exp_f32_e32 v141, v141
	v_fma_f32 v105, v14, s91, v242
	v_add_f32_e32 v240, v124, v240
	global_load_dwordx4 v[152:155], v0, s[10:11]
	v_mfma_f32_32x32x16_bf16 v[32:47], v[172:175], v[92:95], v[32:47]
	v_add_f32_e32 v241, v125, v241
	v_exp_f32_e32 v126, v126
	v_exp_f32_e32 v127, v127
	v_fma_f32 v106, v14, s88, v242
	v_add_f32_e32 v240, v140, v240
	v_add_f32_e32 v241, v141, v241
	global_load_dwordx4 v[156:159], v196, s[10:11]
	s_add_i32 s34, s34, -1
	ds_read_b128 v[160:163], v244 offset:4608
	ds_read_b128 v[164:167], v244 offset:4640
	ds_read_b128 v[168:171], v244 offset:4672
	ds_read_b128 v[172:175], v244 offset:4704
	s_waitcnt lgkmcnt(4)
	v_mfma_f32_32x32x16_bf16 v[16:31], v[224:227], v[80:83], v[16:31]
	v_exp_f32_e32 v142, v142
	v_exp_f32_e32 v143, v143
	v_fma_f32 v107, v14, s89, v242
	v_add_f32_e32 v240, v126, v240
	v_add_f32_e32 v241, v127, v241
	v_fma_f32 v108, v14, s86, v242
	v_mfma_f32_32x32x16_bf16 v[16:31], v[228:231], v[84:87], v[16:31]
	v_fma_f32 v109, v14, s87, v242
	v_fma_f32 v110, v14, s78, v242
	v_fma_f32 v111, v14, s79, v242
	v_mfma_f32_32x32x16_bf16 v[16:31], v[232:235], v[88:91], v[16:31]
	v_mfma_f32_32x32x16_bf16 v[16:31], v[236:239], v[92:95], v[16:31]
	ds_read_b128 v[224:227], v244 offset:0
	ds_read_b128 v[228:231], v244 offset:32
	ds_read_b128 v[232:235], v244 offset:64
	ds_read_b128 v[236:239], v244 offset:96
	s_waitcnt lgkmcnt(4)
	v_mfma_f32_32x32x16_bf16 v[96:111], v[160:163], v[2:5], v[96:111]
	v_mov_b32_e32 v80, v242
	v_add_f32_e32 v81, v14, v242
	v_fma_f32 v82, v14, s62, v242
	v_fma_f32 v83, v14, s63, v242
	v_mfma_f32_32x32x16_bf16 v[96:111], v[164:167], v[6:9], v[96:111]
	v_fma_f32 v84, v14, s64, v242
	v_fma_f32 v85, v14, s65, v242
	v_fma_f32 v86, v14, s66, v242
	v_fma_f32 v87, v14, s67, v242
	v_mfma_f32_32x32x16_bf16 v[96:111], v[168:171], v[10:13], v[96:111]
	v_fma_f32 v88, v14, s68, v242
	v_fma_f32 v89, v14, s69, v242
	v_fma_f32 v90, v14, s70, v242
	v_fma_f32 v91, v14, s71, v242
	v_mfma_f32_32x32x16_bf16 v[96:111], v[172:175], v[144:147], v[96:111]
	v_fma_f32 v92, v14, s72, v242
	v_fma_f32 v93, v14, s73, v242
	v_fma_f32 v94, v14, s76, v242
	v_fma_f32 v95, v14, s77, v242
	ds_read_b128 v[160:163], v251 offset:9216
	ds_read_b128 v[164:167], v251 offset:9248
	ds_read_b128 v[168:171], v251 offset:9280
	ds_read_b128 v[172:175], v251 offset:9312
	s_waitcnt lgkmcnt(4)
	v_mfma_f32_32x32x16_bf16 v[80:95], v[224:227], v[2:5], v[80:95]
	s_nop 0
	v_add_f32_e32 v240, v142, v240
	v_add_f32_e32 v241, v143, v241
	v_cvt_pk_bf16_f32 v112, v112, v113
	v_cvt_pk_bf16_f32 v113, v114, v115
	v_cvt_pk_bf16_f32 v114, v116, v117
	v_mfma_f32_32x32x16_bf16 v[80:95], v[228:231], v[6:9], v[80:95]
	v_cvt_pk_bf16_f32 v115, v118, v119
	v_cvt_pk_bf16_f32 v116, v120, v121
	v_cvt_pk_bf16_f32 v117, v122, v123
	v_cvt_pk_bf16_f32 v118, v124, v125
	v_cvt_pk_bf16_f32 v119, v126, v127
	v_cvt_pk_bf16_f32 v120, v128, v129
	v_mfma_f32_32x32x16_bf16 v[80:95], v[232:235], v[10:13], v[80:95]
	v_cvt_pk_bf16_f32 v121, v130, v131
	v_cvt_pk_bf16_f32 v122, v132, v133
	v_cvt_pk_bf16_f32 v123, v134, v135
	v_cvt_pk_bf16_f32 v124, v136, v137
	v_cvt_pk_bf16_f32 v125, v138, v139
	v_cvt_pk_bf16_f32 v126, v140, v141
	v_mfma_f32_32x32x16_bf16 v[80:95], v[236:239], v[144:147], v[80:95]
	v_cvt_pk_bf16_f32 v127, v142, v143
	v_add_f32_e32 v247, v240, v241
	v_add_f32_e32 v199, v199, v247
	s_branch .Ld_tail1
